# E27: E26 + ret_prompt touches the next chunk's k'/v^T lines with LDS-DMA dword loads right after the chunk-top barrier (L2 prefetch)
# speedup vs baseline: 1.0197x; 1.0081x over previous
.LBB0_1724:
	s_lshl_b32 s1, s37, 7
	s_or_b32 s0, s1, s34
	v_or_b32_e32 v66, s0, v195
	v_readlane_b32 s40, v254, 11
	v_lshl_or_b32 v100, v66, 10, v234
	v_readlane_b32 s42, v254, 13
	v_readlane_b32 s43, v254, 14
	v_or_b32_e32 v68, s0, v197
	v_or_b32_e32 v74, s0, v198
	v_lshl_add_u64 v[66:67], v[100:101], 1, s[42:43]
	v_lshl_or_b32 v100, v68, 10, v234
	v_lshl_add_u64 v[70:71], v[100:101], 1, s[42:43]
	v_lshl_or_b32 v100, v74, 10, v234
	v_or_b32_e32 v76, s0, v199
	v_lshl_add_u64 v[74:75], v[100:101], 1, s[42:43]
	v_lshl_or_b32 v100, v76, 10, v234
	v_or_b32_e32 v82, s0, v200
	v_lshl_add_u64 v[78:79], v[100:101], 1, s[42:43]
	v_lshl_or_b32 v100, v82, 10, v234
	v_or_b32_e32 v84, s0, v201
	v_lshl_add_u64 v[82:83], v[100:101], 1, s[42:43]
	v_lshl_or_b32 v100, v84, 10, v234
	v_or_b32_e32 v91, s0, v202
	v_lshl_add_u64 v[92:93], v[100:101], 1, s[42:43]
	v_lshl_or_b32 v100, v91, 10, v234
	v_add_u32_e32 v91, s0, v203
	global_load_dwordx4 v[66:69], v[66:67], off
	s_nop 0
	global_load_dwordx4 v[70:73], v[70:71], off
	s_nop 0
	global_load_dwordx4 v[74:77], v[74:75], off
	s_nop 0
	global_load_dwordx4 v[78:81], v[78:79], off
	s_nop 0
	global_load_dwordx4 v[82:85], v[82:83], off
	s_nop 0
	global_load_dwordx4 v[156:159], v[92:93], off
	v_lshl_add_u64 v[92:93], v[100:101], 1, s[42:43]
	v_lshl_or_b32 v100, v91, 10, v234
	v_or_b32_e32 v91, s1, v204
	v_lshl_add_u64 v[110:111], v[100:101], 1, s[42:43]
	v_lshlrev_b32_e32 v91, 1, v91
	global_load_dwordx4 v[190:193], v[92:93], off
	global_load_dwordx4 v[242:245], v[110:111], off
	v_add_lshl_u32 v92, v205, s1, 1
	global_load_dwordx4 v[246:249], v91, s[22:23]
	global_load_dwordx4 v[110:113], v92, s[22:23]
	v_mov_b32_e32 v91, v213
	v_mov_b32_e32 v92, v212
	s_mov_b32 s1, 0
	v_readlane_b32 s41, v254, 12
	v_readlane_b32 s44, v254, 15
	v_readlane_b32 s45, v254, 16
	v_readlane_b32 s46, v254, 17
	v_readlane_b32 s47, v254, 18
	s_waitcnt vmcnt(9)
	ds_write_b128 v208, v[66:69] offset:33792
	s_waitcnt vmcnt(8)
	ds_write_b128 v214, v[70:73] offset:33792
	s_waitcnt vmcnt(7)
	ds_write_b128 v208, v[74:77] offset:50688
	s_waitcnt vmcnt(6)
	ds_write_b128 v215, v[78:81] offset:33792
	s_waitcnt vmcnt(5)
	ds_write_b128 v209, v[82:85] offset:33792
	s_waitcnt vmcnt(4)
	ds_write_b128 v216, v[156:159] offset:33792
	s_waitcnt vmcnt(3)
	ds_write_b128 v209, v[190:193] offset:50688
	s_waitcnt vmcnt(2)
	ds_write_b128 v217, v[242:245] offset:33792
	s_waitcnt vmcnt(1)
	ds_write_b128 v218, v[246:249]
	s_waitcnt vmcnt(0)
	ds_write_b128 v219, v[110:113]
	s_waitcnt lgkmcnt(0)
	s_barrier
	s_cmp_ge_u32 s37, 15
	s_cbranch_scc1 .Lmy_rp_nopf
	s_mov_b32 m0, 0x1d000
	s_lshl_b32 s100, s37, 7
	s_add_i32 s100, s100, 0x80
	s_or_b32 s101, s100, s34
	v_or_b32_e32 v242, s101, v195
	v_lshl_or_b32 v242, v242, 10, v234
	v_lshlrev_b32_e32 v242, 1, v242
	global_load_lds_dword v242, s[42:43]
	v_or_b32_e32 v242, s101, v197
	v_lshl_or_b32 v242, v242, 10, v234
	v_lshlrev_b32_e32 v242, 1, v242
	global_load_lds_dword v242, s[42:43]
	v_or_b32_e32 v242, s101, v198
	v_lshl_or_b32 v242, v242, 10, v234
	v_lshlrev_b32_e32 v242, 1, v242
	global_load_lds_dword v242, s[42:43]
	v_or_b32_e32 v242, s101, v199
	v_lshl_or_b32 v242, v242, 10, v234
	v_lshlrev_b32_e32 v242, 1, v242
	global_load_lds_dword v242, s[42:43]
	v_or_b32_e32 v242, s101, v200
	v_lshl_or_b32 v242, v242, 10, v234
	v_lshlrev_b32_e32 v242, 1, v242
	global_load_lds_dword v242, s[42:43]
	v_or_b32_e32 v242, s101, v201
	v_lshl_or_b32 v242, v242, 10, v234
	v_lshlrev_b32_e32 v242, 1, v242
	global_load_lds_dword v242, s[42:43]
	v_or_b32_e32 v242, s101, v202
	v_lshl_or_b32 v242, v242, 10, v234
	v_lshlrev_b32_e32 v242, 1, v242
	global_load_lds_dword v242, s[42:43]
	v_add_u32_e32 v242, s101, v203
	v_lshl_or_b32 v242, v242, 10, v234
	v_lshlrev_b32_e32 v242, 1, v242
	global_load_lds_dword v242, s[42:43]
	v_or_b32_e32 v242, s100, v204
	v_lshlrev_b32_e32 v242, 1, v242
	global_load_lds_dword v242, s[22:23]
	v_add_lshl_u32 v242, v205, s100, 1
	global_load_lds_dword v242, s[22:23]
.Lmy_rp_nopf:
	ds_read_b128 v[66:69], v220
	ds_read_b128 v[70:73], v220 offset:64
	ds_read_b128 v[74:77], v220 offset:8448
	ds_read_b128 v[78:81], v220 offset:8512
	ds_read_b128 v[82:85], v220 offset:16896
	ds_read_b128 v[110:113], v220 offset:16960
	s_waitcnt lgkmcnt(5)
	v_mfma_f32_16x16x32_bf16 v[66:69], v[66:69], v[34:37], 0
	ds_read_b128 v[156:159], v220 offset:25344
	ds_read_b128 v[190:193], v220 offset:25408
	s_waitcnt lgkmcnt(5)
	v_mfma_f32_16x16x32_bf16 v[74:77], v[74:77], v[34:37], 0
	s_waitcnt lgkmcnt(3)
	v_mfma_f32_16x16x32_bf16 v[82:85], v[82:85], v[34:37], 0
	s_waitcnt lgkmcnt(1)
	v_mfma_f32_16x16x32_bf16 v[156:159], v[156:159], v[34:37], 0
	v_mfma_f32_16x16x32_bf16 v[66:69], v[70:73], v[38:41], v[66:69]
	v_mfma_f32_16x16x32_bf16 v[70:73], v[78:81], v[38:41], v[74:77]
	v_mfma_f32_16x16x32_bf16 v[74:77], v[110:113], v[38:41], v[82:85]
	s_nop 2
	ds_read_b128 v[82:85], v220 offset:128
	ds_read_b128 v[110:113], v220 offset:192
	s_waitcnt lgkmcnt(2)
	v_mfma_f32_16x16x32_bf16 v[78:81], v[190:193], v[38:41], v[156:159]
	s_waitcnt lgkmcnt(1)
	v_mfma_f32_16x16x32_bf16 v[66:69], v[82:85], v[42:45], v[66:69]
	ds_read_b128 v[82:85], v220 offset:8576
	ds_read_b128 v[156:159], v220 offset:8640
	s_waitcnt lgkmcnt(1)
	v_mfma_f32_16x16x32_bf16 v[70:73], v[82:85], v[42:45], v[70:73]
	ds_read_b128 v[82:85], v220 offset:17024
	ds_read_b128 v[190:193], v220 offset:17088
	s_waitcnt lgkmcnt(1)
	v_mfma_f32_16x16x32_bf16 v[74:77], v[82:85], v[42:45], v[74:77]
	ds_read_b128 v[82:85], v220 offset:25472
	ds_read_b128 v[242:245], v220 offset:25536
	s_waitcnt lgkmcnt(1)
	v_mfma_f32_16x16x32_bf16 v[78:81], v[82:85], v[42:45], v[78:81]
	v_mfma_f32_16x16x32_bf16 v[66:69], v[110:113], v[46:49], v[66:69]
	ds_read_b128 v[82:85], v220 offset:256
	ds_read_b128 v[110:113], v220 offset:320
	v_mfma_f32_16x16x32_bf16 v[70:73], v[156:159], v[46:49], v[70:73]
	s_waitcnt lgkmcnt(1)
	v_mfma_f32_16x16x32_bf16 v[66:69], v[82:85], v[50:53], v[66:69]
	ds_read_b128 v[82:85], v220 offset:8704
	ds_read_b128 v[156:159], v220 offset:8768
	v_mfma_f32_16x16x32_bf16 v[74:77], v[190:193], v[46:49], v[74:77]
	s_waitcnt lgkmcnt(1)
	v_mfma_f32_16x16x32_bf16 v[70:73], v[82:85], v[50:53], v[70:73]
	ds_read_b128 v[82:85], v220 offset:17152
	ds_read_b128 v[190:193], v220 offset:17216
	v_mfma_f32_16x16x32_bf16 v[78:81], v[242:245], v[46:49], v[78:81]
	s_waitcnt lgkmcnt(1)
	v_mfma_f32_16x16x32_bf16 v[74:77], v[82:85], v[50:53], v[74:77]
	ds_read_b128 v[82:85], v220 offset:25600
	ds_read_b128 v[242:245], v220 offset:25664
	s_waitcnt lgkmcnt(1)
	v_mfma_f32_16x16x32_bf16 v[78:81], v[82:85], v[50:53], v[78:81]
	v_mfma_f32_16x16x32_bf16 v[66:69], v[110:113], v[54:57], v[66:69]
	ds_read_b128 v[82:85], v220 offset:384
	ds_read_b128 v[110:113], v220 offset:448
	v_mfma_f32_16x16x32_bf16 v[70:73], v[156:159], v[54:57], v[70:73]
	s_waitcnt lgkmcnt(1)
	v_mfma_f32_16x16x32_bf16 v[66:69], v[82:85], v[58:61], v[66:69]
	ds_read_b128 v[82:85], v220 offset:8832
	ds_read_b128 v[156:159], v220 offset:8896
	v_mfma_f32_16x16x32_bf16 v[74:77], v[190:193], v[54:57], v[74:77]
	s_waitcnt lgkmcnt(1)
	v_mfma_f32_16x16x32_bf16 v[70:73], v[82:85], v[58:61], v[70:73]
	ds_read_b128 v[82:85], v220 offset:17280
	ds_read_b128 v[190:193], v220 offset:17344
	v_mfma_f32_16x16x32_bf16 v[78:81], v[242:245], v[54:57], v[78:81]
	s_waitcnt lgkmcnt(1)
	v_mfma_f32_16x16x32_bf16 v[82:85], v[82:85], v[58:61], v[74:77]
	s_nop 2
	ds_read_b128 v[74:77], v220 offset:25728
	ds_read_b128 v[242:245], v220 offset:25792
	s_waitcnt lgkmcnt(1)
	v_mfma_f32_16x16x32_bf16 v[246:249], v[74:77], v[58:61], v[78:81]
	v_mfma_f32_16x16x32_bf16 v[78:81], v[110:113], v[62:65], v[66:69]
	v_mfma_f32_16x16x32_bf16 v[74:77], v[156:159], v[62:65], v[70:73]
	v_mfma_f32_16x16x32_bf16 v[70:73], v[190:193], v[62:65], v[82:85]
	s_waitcnt lgkmcnt(0)
	v_mfma_f32_16x16x32_bf16 v[66:69], v[242:245], v[62:65], v[246:249]
